# phase 23 lru_final: chunk-prefix loops batched (16 chunk loads in flight + vmcnt ladder) instead of load-wait-fma per chunk
# speedup vs baseline: 1.0103x; 1.0103x over previous
.LBB0_1535:
	s_cmp_ge_i32 s48, s46
	v_lshlrev_b32_e32 v2, 2, v2
	s_cbranch_scc1 .LBB0_1538
	s_mov_b32 s24, s48
	s_add_i32 s25, s46, -1
.Llru_pf_batch:
	s_mov_b32 s0, s24
	s_min_i32 s0, s0, s25
	s_lshl_b32 s0, s0, 12
	s_add_u32 s50, s6, s0
	s_addc_u32 s51, s7, 0
	global_load_dwordx2 v[64:65], v2, s[50:51]
	s_add_u32 s50, s8, s0
	s_addc_u32 s51, s9, 0
	global_load_dwordx2 v[66:67], v2, s[50:51]
	s_add_i32 s0, s24, 1
	s_min_i32 s0, s0, s25
	s_lshl_b32 s0, s0, 12
	s_add_u32 s50, s6, s0
	s_addc_u32 s51, s7, 0
	global_load_dwordx2 v[68:69], v2, s[50:51]
	s_add_u32 s50, s8, s0
	s_addc_u32 s51, s9, 0
	global_load_dwordx2 v[70:71], v2, s[50:51]
	s_add_i32 s0, s24, 2
	s_min_i32 s0, s0, s25
	s_lshl_b32 s0, s0, 12
	s_add_u32 s50, s6, s0
	s_addc_u32 s51, s7, 0
	global_load_dwordx2 v[72:73], v2, s[50:51]
	s_add_u32 s50, s8, s0
	s_addc_u32 s51, s9, 0
	global_load_dwordx2 v[74:75], v2, s[50:51]
	s_add_i32 s0, s24, 3
	s_min_i32 s0, s0, s25
	s_lshl_b32 s0, s0, 12
	s_add_u32 s50, s6, s0
	s_addc_u32 s51, s7, 0
	global_load_dwordx2 v[76:77], v2, s[50:51]
	s_add_u32 s50, s8, s0
	s_addc_u32 s51, s9, 0
	global_load_dwordx2 v[78:79], v2, s[50:51]
	s_add_i32 s0, s24, 4
	s_min_i32 s0, s0, s25
	s_lshl_b32 s0, s0, 12
	s_add_u32 s50, s6, s0
	s_addc_u32 s51, s7, 0
	global_load_dwordx2 v[80:81], v2, s[50:51]
	s_add_u32 s50, s8, s0
	s_addc_u32 s51, s9, 0
	global_load_dwordx2 v[82:83], v2, s[50:51]
	s_add_i32 s0, s24, 5
	s_min_i32 s0, s0, s25
	s_lshl_b32 s0, s0, 12
	s_add_u32 s50, s6, s0
	s_addc_u32 s51, s7, 0
	global_load_dwordx2 v[84:85], v2, s[50:51]
	s_add_u32 s50, s8, s0
	s_addc_u32 s51, s9, 0
	global_load_dwordx2 v[86:87], v2, s[50:51]
	s_add_i32 s0, s24, 6
	s_min_i32 s0, s0, s25
	s_lshl_b32 s0, s0, 12
	s_add_u32 s50, s6, s0
	s_addc_u32 s51, s7, 0
	global_load_dwordx2 v[88:89], v2, s[50:51]
	s_add_u32 s50, s8, s0
	s_addc_u32 s51, s9, 0
	global_load_dwordx2 v[90:91], v2, s[50:51]
	s_add_i32 s0, s24, 7
	s_min_i32 s0, s0, s25
	s_lshl_b32 s0, s0, 12
	s_add_u32 s50, s6, s0
	s_addc_u32 s51, s7, 0
	global_load_dwordx2 v[92:93], v2, s[50:51]
	s_add_u32 s50, s8, s0
	s_addc_u32 s51, s9, 0
	global_load_dwordx2 v[94:95], v2, s[50:51]
	s_add_i32 s0, s24, 8
	s_min_i32 s0, s0, s25
	s_lshl_b32 s0, s0, 12
	s_add_u32 s50, s6, s0
	s_addc_u32 s51, s7, 0
	global_load_dwordx2 v[96:97], v2, s[50:51]
	s_add_u32 s50, s8, s0
	s_addc_u32 s51, s9, 0
	global_load_dwordx2 v[98:99], v2, s[50:51]
	s_add_i32 s0, s24, 9
	s_min_i32 s0, s0, s25
	s_lshl_b32 s0, s0, 12
	s_add_u32 s50, s6, s0
	s_addc_u32 s51, s7, 0
	global_load_dwordx2 v[100:101], v2, s[50:51]
	s_add_u32 s50, s8, s0
	s_addc_u32 s51, s9, 0
	global_load_dwordx2 v[102:103], v2, s[50:51]
	s_add_i32 s0, s24, 10
	s_min_i32 s0, s0, s25
	s_lshl_b32 s0, s0, 12
	s_add_u32 s50, s6, s0
	s_addc_u32 s51, s7, 0
	global_load_dwordx2 v[104:105], v2, s[50:51]
	s_add_u32 s50, s8, s0
	s_addc_u32 s51, s9, 0
	global_load_dwordx2 v[106:107], v2, s[50:51]
	s_add_i32 s0, s24, 11
	s_min_i32 s0, s0, s25
	s_lshl_b32 s0, s0, 12
	s_add_u32 s50, s6, s0
	s_addc_u32 s51, s7, 0
	global_load_dwordx2 v[108:109], v2, s[50:51]
	s_add_u32 s50, s8, s0
	s_addc_u32 s51, s9, 0
	global_load_dwordx2 v[110:111], v2, s[50:51]
	s_add_i32 s0, s24, 12
	s_min_i32 s0, s0, s25
	s_lshl_b32 s0, s0, 12
	s_add_u32 s50, s6, s0
	s_addc_u32 s51, s7, 0
	global_load_dwordx2 v[112:113], v2, s[50:51]
	s_add_u32 s50, s8, s0
	s_addc_u32 s51, s9, 0
	global_load_dwordx2 v[114:115], v2, s[50:51]
	s_add_i32 s0, s24, 13
	s_min_i32 s0, s0, s25
	s_lshl_b32 s0, s0, 12
	s_add_u32 s50, s6, s0
	s_addc_u32 s51, s7, 0
	global_load_dwordx2 v[116:117], v2, s[50:51]
	s_add_u32 s50, s8, s0
	s_addc_u32 s51, s9, 0
	global_load_dwordx2 v[118:119], v2, s[50:51]
	s_add_i32 s0, s24, 14
	s_min_i32 s0, s0, s25
	s_lshl_b32 s0, s0, 12
	s_add_u32 s50, s6, s0
	s_addc_u32 s51, s7, 0
	global_load_dwordx2 v[120:121], v2, s[50:51]
	s_add_u32 s50, s8, s0
	s_addc_u32 s51, s9, 0
	global_load_dwordx2 v[122:123], v2, s[50:51]
	s_add_i32 s0, s24, 15
	s_min_i32 s0, s0, s25
	s_lshl_b32 s0, s0, 12
	s_add_u32 s50, s6, s0
	s_addc_u32 s51, s7, 0
	global_load_dwordx2 v[124:125], v2, s[50:51]
	s_add_u32 s50, s8, s0
	s_addc_u32 s51, s9, 0
	global_load_dwordx2 v[126:127], v2, s[50:51]
	s_waitcnt vmcnt(30)
	v_pk_fma_f32 v[6:7], v[6:7], v[64:65], v[66:67]
	s_add_i32 s24, s24, 1
	s_cmp_ge_i32 s24, s46
	s_cbranch_scc1 .Llru_pf_done
	s_waitcnt vmcnt(28)
	v_pk_fma_f32 v[6:7], v[6:7], v[68:69], v[70:71]
	s_add_i32 s24, s24, 1
	s_cmp_ge_i32 s24, s46
	s_cbranch_scc1 .Llru_pf_done
	s_waitcnt vmcnt(26)
	v_pk_fma_f32 v[6:7], v[6:7], v[72:73], v[74:75]
	s_add_i32 s24, s24, 1
	s_cmp_ge_i32 s24, s46
	s_cbranch_scc1 .Llru_pf_done
	s_waitcnt vmcnt(24)
	v_pk_fma_f32 v[6:7], v[6:7], v[76:77], v[78:79]
	s_add_i32 s24, s24, 1
	s_cmp_ge_i32 s24, s46
	s_cbranch_scc1 .Llru_pf_done
	s_waitcnt vmcnt(22)
	v_pk_fma_f32 v[6:7], v[6:7], v[80:81], v[82:83]
	s_add_i32 s24, s24, 1
	s_cmp_ge_i32 s24, s46
	s_cbranch_scc1 .Llru_pf_done
	s_waitcnt vmcnt(20)
	v_pk_fma_f32 v[6:7], v[6:7], v[84:85], v[86:87]
	s_add_i32 s24, s24, 1
	s_cmp_ge_i32 s24, s46
	s_cbranch_scc1 .Llru_pf_done
	s_waitcnt vmcnt(18)
	v_pk_fma_f32 v[6:7], v[6:7], v[88:89], v[90:91]
	s_add_i32 s24, s24, 1
	s_cmp_ge_i32 s24, s46
	s_cbranch_scc1 .Llru_pf_done
	s_waitcnt vmcnt(16)
	v_pk_fma_f32 v[6:7], v[6:7], v[92:93], v[94:95]
	s_add_i32 s24, s24, 1
	s_cmp_ge_i32 s24, s46
	s_cbranch_scc1 .Llru_pf_done
	s_waitcnt vmcnt(14)
	v_pk_fma_f32 v[6:7], v[6:7], v[96:97], v[98:99]
	s_add_i32 s24, s24, 1
	s_cmp_ge_i32 s24, s46
	s_cbranch_scc1 .Llru_pf_done
	s_waitcnt vmcnt(12)
	v_pk_fma_f32 v[6:7], v[6:7], v[100:101], v[102:103]
	s_add_i32 s24, s24, 1
	s_cmp_ge_i32 s24, s46
	s_cbranch_scc1 .Llru_pf_done
	s_waitcnt vmcnt(10)
	v_pk_fma_f32 v[6:7], v[6:7], v[104:105], v[106:107]
	s_add_i32 s24, s24, 1
	s_cmp_ge_i32 s24, s46
	s_cbranch_scc1 .Llru_pf_done
	s_waitcnt vmcnt(8)
	v_pk_fma_f32 v[6:7], v[6:7], v[108:109], v[110:111]
	s_add_i32 s24, s24, 1
	s_cmp_ge_i32 s24, s46
	s_cbranch_scc1 .Llru_pf_done
	s_waitcnt vmcnt(6)
	v_pk_fma_f32 v[6:7], v[6:7], v[112:113], v[114:115]
	s_add_i32 s24, s24, 1
	s_cmp_ge_i32 s24, s46
	s_cbranch_scc1 .Llru_pf_done
	s_waitcnt vmcnt(4)
	v_pk_fma_f32 v[6:7], v[6:7], v[116:117], v[118:119]
	s_add_i32 s24, s24, 1
	s_cmp_ge_i32 s24, s46
	s_cbranch_scc1 .Llru_pf_done
	s_waitcnt vmcnt(2)
	v_pk_fma_f32 v[6:7], v[6:7], v[120:121], v[122:123]
	s_add_i32 s24, s24, 1
	s_cmp_ge_i32 s24, s46
	s_cbranch_scc1 .Llru_pf_done
	s_waitcnt vmcnt(0)
	v_pk_fma_f32 v[6:7], v[6:7], v[124:125], v[126:127]
	s_add_i32 s24, s24, 1
	s_cmp_ge_i32 s24, s46
	s_cbranch_scc0 .Llru_pf_batch
.Llru_pf_done:
.LBB0_1538:
	s_cmp_le_i32 s49, s46
	s_cbranch_scc1 .LBB0_1541
	s_mov_b32 s24, s49
	s_add_i32 s25, s46, 1
.Llru_pb_batch:
	s_mov_b32 s0, s24
	s_max_i32 s0, s0, s25
	s_lshl_b32 s0, s0, 12
	s_add_i32 s0, s0, 0x100000
	s_add_u32 s50, s6, s0
	s_addc_u32 s51, s7, 0
	global_load_dwordx2 v[64:65], v2, s[50:51]
	s_add_u32 s50, s8, s0
	s_addc_u32 s51, s9, 0
	global_load_dwordx2 v[66:67], v2, s[50:51]
	s_add_i32 s0, s24, -1
	s_max_i32 s0, s0, s25
	s_lshl_b32 s0, s0, 12
	s_add_i32 s0, s0, 0x100000
	s_add_u32 s50, s6, s0
	s_addc_u32 s51, s7, 0
	global_load_dwordx2 v[68:69], v2, s[50:51]
	s_add_u32 s50, s8, s0
	s_addc_u32 s51, s9, 0
	global_load_dwordx2 v[70:71], v2, s[50:51]
	s_add_i32 s0, s24, -2
	s_max_i32 s0, s0, s25
	s_lshl_b32 s0, s0, 12
	s_add_i32 s0, s0, 0x100000
	s_add_u32 s50, s6, s0
	s_addc_u32 s51, s7, 0
	global_load_dwordx2 v[72:73], v2, s[50:51]
	s_add_u32 s50, s8, s0
	s_addc_u32 s51, s9, 0
	global_load_dwordx2 v[74:75], v2, s[50:51]
	s_add_i32 s0, s24, -3
	s_max_i32 s0, s0, s25
	s_lshl_b32 s0, s0, 12
	s_add_i32 s0, s0, 0x100000
	s_add_u32 s50, s6, s0
	s_addc_u32 s51, s7, 0
	global_load_dwordx2 v[76:77], v2, s[50:51]
	s_add_u32 s50, s8, s0
	s_addc_u32 s51, s9, 0
	global_load_dwordx2 v[78:79], v2, s[50:51]
	s_add_i32 s0, s24, -4
	s_max_i32 s0, s0, s25
	s_lshl_b32 s0, s0, 12
	s_add_i32 s0, s0, 0x100000
	s_add_u32 s50, s6, s0
	s_addc_u32 s51, s7, 0
	global_load_dwordx2 v[80:81], v2, s[50:51]
	s_add_u32 s50, s8, s0
	s_addc_u32 s51, s9, 0
	global_load_dwordx2 v[82:83], v2, s[50:51]
	s_add_i32 s0, s24, -5
	s_max_i32 s0, s0, s25
	s_lshl_b32 s0, s0, 12
	s_add_i32 s0, s0, 0x100000
	s_add_u32 s50, s6, s0
	s_addc_u32 s51, s7, 0
	global_load_dwordx2 v[84:85], v2, s[50:51]
	s_add_u32 s50, s8, s0
	s_addc_u32 s51, s9, 0
	global_load_dwordx2 v[86:87], v2, s[50:51]
	s_add_i32 s0, s24, -6
	s_max_i32 s0, s0, s25
	s_lshl_b32 s0, s0, 12
	s_add_i32 s0, s0, 0x100000
	s_add_u32 s50, s6, s0
	s_addc_u32 s51, s7, 0
	global_load_dwordx2 v[88:89], v2, s[50:51]
	s_add_u32 s50, s8, s0
	s_addc_u32 s51, s9, 0
	global_load_dwordx2 v[90:91], v2, s[50:51]
	s_add_i32 s0, s24, -7
	s_max_i32 s0, s0, s25
	s_lshl_b32 s0, s0, 12
	s_add_i32 s0, s0, 0x100000
	s_add_u32 s50, s6, s0
	s_addc_u32 s51, s7, 0
	global_load_dwordx2 v[92:93], v2, s[50:51]
	s_add_u32 s50, s8, s0
	s_addc_u32 s51, s9, 0
	global_load_dwordx2 v[94:95], v2, s[50:51]
	s_add_i32 s0, s24, -8
	s_max_i32 s0, s0, s25
	s_lshl_b32 s0, s0, 12
	s_add_i32 s0, s0, 0x100000
	s_add_u32 s50, s6, s0
	s_addc_u32 s51, s7, 0
	global_load_dwordx2 v[96:97], v2, s[50:51]
	s_add_u32 s50, s8, s0
	s_addc_u32 s51, s9, 0
	global_load_dwordx2 v[98:99], v2, s[50:51]
	s_add_i32 s0, s24, -9
	s_max_i32 s0, s0, s25
	s_lshl_b32 s0, s0, 12
	s_add_i32 s0, s0, 0x100000
	s_add_u32 s50, s6, s0
	s_addc_u32 s51, s7, 0
	global_load_dwordx2 v[100:101], v2, s[50:51]
	s_add_u32 s50, s8, s0
	s_addc_u32 s51, s9, 0
	global_load_dwordx2 v[102:103], v2, s[50:51]
	s_add_i32 s0, s24, -10
	s_max_i32 s0, s0, s25
	s_lshl_b32 s0, s0, 12
	s_add_i32 s0, s0, 0x100000
	s_add_u32 s50, s6, s0
	s_addc_u32 s51, s7, 0
	global_load_dwordx2 v[104:105], v2, s[50:51]
	s_add_u32 s50, s8, s0
	s_addc_u32 s51, s9, 0
	global_load_dwordx2 v[106:107], v2, s[50:51]
	s_add_i32 s0, s24, -11
	s_max_i32 s0, s0, s25
	s_lshl_b32 s0, s0, 12
	s_add_i32 s0, s0, 0x100000
	s_add_u32 s50, s6, s0
	s_addc_u32 s51, s7, 0
	global_load_dwordx2 v[108:109], v2, s[50:51]
	s_add_u32 s50, s8, s0
	s_addc_u32 s51, s9, 0
	global_load_dwordx2 v[110:111], v2, s[50:51]
	s_add_i32 s0, s24, -12
	s_max_i32 s0, s0, s25
	s_lshl_b32 s0, s0, 12
	s_add_i32 s0, s0, 0x100000
	s_add_u32 s50, s6, s0
	s_addc_u32 s51, s7, 0
	global_load_dwordx2 v[112:113], v2, s[50:51]
	s_add_u32 s50, s8, s0
	s_addc_u32 s51, s9, 0
	global_load_dwordx2 v[114:115], v2, s[50:51]
	s_add_i32 s0, s24, -13
	s_max_i32 s0, s0, s25
	s_lshl_b32 s0, s0, 12
	s_add_i32 s0, s0, 0x100000
	s_add_u32 s50, s6, s0
	s_addc_u32 s51, s7, 0
	global_load_dwordx2 v[116:117], v2, s[50:51]
	s_add_u32 s50, s8, s0
	s_addc_u32 s51, s9, 0
	global_load_dwordx2 v[118:119], v2, s[50:51]
	s_add_i32 s0, s24, -14
	s_max_i32 s0, s0, s25
	s_lshl_b32 s0, s0, 12
	s_add_i32 s0, s0, 0x100000
	s_add_u32 s50, s6, s0
	s_addc_u32 s51, s7, 0
	global_load_dwordx2 v[120:121], v2, s[50:51]
	s_add_u32 s50, s8, s0
	s_addc_u32 s51, s9, 0
	global_load_dwordx2 v[122:123], v2, s[50:51]
	s_add_i32 s0, s24, -15
	s_max_i32 s0, s0, s25
	s_lshl_b32 s0, s0, 12
	s_add_i32 s0, s0, 0x100000
	s_add_u32 s50, s6, s0
	s_addc_u32 s51, s7, 0
	global_load_dwordx2 v[124:125], v2, s[50:51]
	s_add_u32 s50, s8, s0
	s_addc_u32 s51, s9, 0
	global_load_dwordx2 v[126:127], v2, s[50:51]
	s_waitcnt vmcnt(30)
	v_pk_fma_f32 v[4:5], v[4:5], v[64:65], v[66:67]
	s_add_i32 s24, s24, -1
	s_cmp_le_i32 s24, s46
	s_cbranch_scc1 .Llru_pb_done
	s_waitcnt vmcnt(28)
	v_pk_fma_f32 v[4:5], v[4:5], v[68:69], v[70:71]
	s_add_i32 s24, s24, -1
	s_cmp_le_i32 s24, s46
	s_cbranch_scc1 .Llru_pb_done
	s_waitcnt vmcnt(26)
	v_pk_fma_f32 v[4:5], v[4:5], v[72:73], v[74:75]
	s_add_i32 s24, s24, -1
	s_cmp_le_i32 s24, s46
	s_cbranch_scc1 .Llru_pb_done
	s_waitcnt vmcnt(24)
	v_pk_fma_f32 v[4:5], v[4:5], v[76:77], v[78:79]
	s_add_i32 s24, s24, -1
	s_cmp_le_i32 s24, s46
	s_cbranch_scc1 .Llru_pb_done
	s_waitcnt vmcnt(22)
	v_pk_fma_f32 v[4:5], v[4:5], v[80:81], v[82:83]
	s_add_i32 s24, s24, -1
	s_cmp_le_i32 s24, s46
	s_cbranch_scc1 .Llru_pb_done
	s_waitcnt vmcnt(20)
	v_pk_fma_f32 v[4:5], v[4:5], v[84:85], v[86:87]
	s_add_i32 s24, s24, -1
	s_cmp_le_i32 s24, s46
	s_cbranch_scc1 .Llru_pb_done
	s_waitcnt vmcnt(18)
	v_pk_fma_f32 v[4:5], v[4:5], v[88:89], v[90:91]
	s_add_i32 s24, s24, -1
	s_cmp_le_i32 s24, s46
	s_cbranch_scc1 .Llru_pb_done
	s_waitcnt vmcnt(16)
	v_pk_fma_f32 v[4:5], v[4:5], v[92:93], v[94:95]
	s_add_i32 s24, s24, -1
	s_cmp_le_i32 s24, s46
	s_cbranch_scc1 .Llru_pb_done
	s_waitcnt vmcnt(14)
	v_pk_fma_f32 v[4:5], v[4:5], v[96:97], v[98:99]
	s_add_i32 s24, s24, -1
	s_cmp_le_i32 s24, s46
	s_cbranch_scc1 .Llru_pb_done
	s_waitcnt vmcnt(12)
	v_pk_fma_f32 v[4:5], v[4:5], v[100:101], v[102:103]
	s_add_i32 s24, s24, -1
	s_cmp_le_i32 s24, s46
	s_cbranch_scc1 .Llru_pb_done
	s_waitcnt vmcnt(10)
	v_pk_fma_f32 v[4:5], v[4:5], v[104:105], v[106:107]
	s_add_i32 s24, s24, -1
	s_cmp_le_i32 s24, s46
	s_cbranch_scc1 .Llru_pb_done
	s_waitcnt vmcnt(8)
	v_pk_fma_f32 v[4:5], v[4:5], v[108:109], v[110:111]
	s_add_i32 s24, s24, -1
	s_cmp_le_i32 s24, s46
	s_cbranch_scc1 .Llru_pb_done
	s_waitcnt vmcnt(6)
	v_pk_fma_f32 v[4:5], v[4:5], v[112:113], v[114:115]
	s_add_i32 s24, s24, -1
	s_cmp_le_i32 s24, s46
	s_cbranch_scc1 .Llru_pb_done
	s_waitcnt vmcnt(4)
	v_pk_fma_f32 v[4:5], v[4:5], v[116:117], v[118:119]
	s_add_i32 s24, s24, -1
	s_cmp_le_i32 s24, s46
	s_cbranch_scc1 .Llru_pb_done
	s_waitcnt vmcnt(2)
	v_pk_fma_f32 v[4:5], v[4:5], v[120:121], v[122:123]
	s_add_i32 s24, s24, -1
	s_cmp_le_i32 s24, s46
	s_cbranch_scc1 .Llru_pb_done
	s_waitcnt vmcnt(0)
	v_pk_fma_f32 v[4:5], v[4:5], v[124:125], v[126:127]
	s_add_i32 s24, s24, -1
	s_cmp_le_i32 s24, s46
	s_cbranch_scc0 .Llru_pb_batch
.Llru_pb_done:
.LBB0_1541:
	s_lshl_b32 s0, s11, 1
	s_and_b32 s0, s0, 0x200
	v_add_u32_e32 v1, s0, v13
	s_lshl_b32 s0, s46, 6
	s_ashr_i32 s1, s0, 31
	s_lshl_b64 s[0:1], s[0:1], 11
	v_lshl_or_b32 v8, v1, 1, s0
	v_mov_b32_e32 v9, s1
	v_lshl_add_u64 v[10:11], s[14:15], 0, v[8:9]
	s_mov_b64 s[24:25], 0
	v_mov_b32_e32 v1, v12
